# v98 + sc1 (agent-scope, written through) on the DA / SB output stores to MIX
# baseline (speedup 1.0000x reference)
; #define LAS __attribute__((address_space(3)))
; #define GAS __attribute__((address_space(1)))
; __host__ __device__ __forceinline__ size_t bl1024(size_t row, int col) { return ((row >> 5) * 128 + (size_t)(col >> 3)) * 256 + (row & 31) * 8 + (col & 7); }
; __device__ __forceinline__ void da_phase(LAS unsigned char* lds, const GAS f16* __restrict__ kv, const GAS f16* __restrict__ qg, GAS f16* __restrict__ mixed, int vcu, int G, ...
;     ...
;         asm volatile("s_waitcnt lgkmcnt(0)\n\ts_barrier" ::: "memory");
;         ss += ssx[(c ^ 1) * 32 + l31];
;         const float rn = __builtin_amdgcn_rsqf(ss * (1.0f / 128.0f) + RMS_EPS) * osc;
;         {
;             const LAS float* sgl = (const LAS float*)(lds + DA_SUBG) + 32 * dlo + 4 * hi;
;             GAS f16* Op = mixed + bl1024(grow, 512 + U.h * 128 + 32 * dlo);
;             u32x2 gv[8]; unpack_groups(gr, gv);
; #pragma unroll
;             for (int pr = 0; pr < 2; ++pr) {
;                 u32x2 wv[2];
; #pragma unroll
;                 for (int e = 0; e < 2; ++e) { const int rg4 = 2 * pr + e; const h4 g = __builtin_bit_cast(h4, gv[rg4]); const f32x4 sg = *(const LAS f32x4*)(sgl + 8 * rg4);
;                     wv[e].x = pkh(ya[4 * rg4] * rn * sg[0] * (float)g[0], ya[4 * rg4 + 1] * rn * sg[1] * (float)g[1]);
;                     wv[e].y = pkh(ya[4 * rg4 + 2] * rn * sg[2] * (float)g[2], ya[4 * rg4 + 3] * rn * sg[3] * (float)g[3]); }
;                 st_groups2_bl(Op, hi, pr, wv[0], wv[1]);
;             }
; #pragma unroll
;             for (int pr = 0; pr < 2; ++pr) {
;                 u32x2 wv[2];
; #pragma unroll
;                 for (int e = 0; e < 2; ++e) { const int rg4 = 2 * pr + e; const h4 g = __builtin_bit_cast(h4, gv[4 + rg4]); const f32x4 sg = *(const LAS f32x4*)(sgl + 32 + 8 * rg4);
;                     wv[e].x = pkh(yb[4 * rg4] * rn * sg[0] * (float)g[0], yb[4 * rg4 + 1] * rn * sg[1] * (float)g[1]);
;                     wv[e].y = pkh(yb[4 * rg4 + 2] * rn * sg[2] * (float)g[2], yb[4 * rg4 + 3] * rn * sg[3] * (float)g[3]); }
;                 st_groups2_bl(Op, hi, 2 + pr, wv[0], wv[1]);
;             }
.LBB0_490:
	s_or_b64 exec, exec, s[4:5]
	s_waitcnt lgkmcnt(0)
	s_barrier
	ds_read_b32 v33, v198
	ds_read_b128 v[42:45], v201
	ds_read_b128 v[46:49], v201 offset:32
	s_waitcnt vmcnt(3)
	v_mov_b32_e32 v50, v82
	s_nop 1
	v_permlane32_swap_b32_e32 v80, v50
	s_waitcnt lgkmcnt(2)
	v_add_f32_e32 v32, v32, v33
	v_fmamk_f32 v32, v32, 0x3c000000, v211
	v_rsq_f32_e32 v32, v32
	s_waitcnt vmcnt(0)
	v_mov_b32_e32 v33, v70
	s_nop 1
	v_permlane32_swap_b32_e32 v68, v33
	v_mul_f32_e32 v32, v172, v32
	v_pk_mul_f32 v[24:25], v[24:25], v[32:33] op_sel_hi:[1,0]
	v_mov_b32_e32 v51, v83
	s_waitcnt lgkmcnt(1)
	v_pk_mul_f32 v[24:25], v[24:25], v[42:43]
	v_cvt_f32_f16_e32 v42, v80
	v_cvt_f32_f16_sdwa v43, v80 dst_sel:DWORD dst_unused:UNUSED_PAD src0_sel:WORD_1
	v_permlane32_swap_b32_e32 v81, v51
	v_pk_mul_f32 v[16:17], v[16:17], v[32:33] op_sel_hi:[1,0]
	v_pk_mul_f32 v[24:25], v[24:25], v[42:43]
	v_pk_mul_f32 v[16:17], v[16:17], v[44:45]
	v_cvt_pk_f16_f32 v42, v24, v25
	v_cvt_f32_f16_e32 v24, v81
	v_cvt_f32_f16_sdwa v25, v81 dst_sel:DWORD dst_unused:UNUSED_PAD src0_sel:WORD_1
	v_mov_b32_e32 v52, v78
	v_mov_b32_e32 v53, v79
	s_nop 0
	v_permlane32_swap_b32_e32 v76, v52
	v_pk_mul_f32 v[16:17], v[16:17], v[24:25]
	v_permlane32_swap_b32_e32 v77, v53
	v_cvt_pk_f16_f32 v43, v16, v17
	v_pk_mul_f32 v[16:17], v[20:21], v[32:33] op_sel_hi:[1,0]
	v_cvt_f32_f16_e32 v20, v50
	v_cvt_f32_f16_sdwa v21, v50 dst_sel:DWORD dst_unused:UNUSED_PAD src0_sel:WORD_1
	s_waitcnt lgkmcnt(0)
	v_pk_mul_f32 v[16:17], v[16:17], v[46:47]
	v_pk_mul_f32 v[24:25], v[30:31], v[32:33] op_sel_hi:[1,0]
	v_pk_mul_f32 v[22:23], v[22:23], v[32:33] op_sel_hi:[1,0]
	v_pk_mul_f32 v[16:17], v[16:17], v[20:21]
	s_add_i32 s4, s0, 0x200
	v_cvt_pk_f16_f32 v44, v16, v17
	v_pk_mul_f32 v[16:17], v[18:19], v[32:33] op_sel_hi:[1,0]
	v_cvt_f32_f16_e32 v18, v51
	v_cvt_f32_f16_sdwa v19, v51 dst_sel:DWORD dst_unused:UNUSED_PAD src0_sel:WORD_1
	v_pk_mul_f32 v[16:17], v[16:17], v[48:49]
	s_lshl_b64 s[0:1], s[6:7], 2
	s_ashr_i32 s4, s4, 3
	v_pk_mul_f32 v[16:17], v[16:17], v[18:19]
	ds_read_b128 v[18:21], v201 offset:64
	s_and_b32 s1, s1, 0x7fffff
	s_and_b32 s0, s0, 0xffffff80
	s_ashr_i32 s5, s4, 31
	s_add_u32 s0, s0, s4
	s_waitcnt lgkmcnt(0)
	v_pk_mul_f32 v[18:19], v[24:25], v[18:19]
	v_cvt_f32_f16_e32 v24, v76
	v_cvt_f32_f16_sdwa v25, v76 dst_sel:DWORD dst_unused:UNUSED_PAD src0_sel:WORD_1
	v_pk_mul_f32 v[20:21], v[22:23], v[20:21]
	v_cvt_f32_f16_e32 v22, v77
	v_cvt_f32_f16_sdwa v23, v77 dst_sel:DWORD dst_unused:UNUSED_PAD src0_sel:WORD_1
	v_pk_mul_f32 v[18:19], v[18:19], v[24:25]
	v_pk_mul_f32 v[24:25], v[34:35], v[32:33] op_sel_hi:[1,0]
	v_cvt_pk_f16_f32 v18, v18, v19
	v_pk_mul_f32 v[20:21], v[20:21], v[22:23]
	s_addc_u32 s1, s1, s5
	v_cvt_pk_f16_f32 v19, v20, v21
	ds_read_b128 v[20:23], v201 offset:96
	s_lshl_b64 s[0:1], s[0:1], 9
	s_add_u32 s0, s33, s0
	s_addc_u32 s1, s26, s1
	v_lshl_add_u64 v[38:39], s[0:1], 0, v[2:3]
	s_waitcnt lgkmcnt(0)
	v_pk_mul_f32 v[20:21], v[24:25], v[20:21]
	v_cvt_f32_f16_e32 v24, v52
	v_cvt_f32_f16_sdwa v25, v52 dst_sel:DWORD dst_unused:UNUSED_PAD src0_sel:WORD_1
	v_mov_b32_e32 v159, v3
	v_cvt_pk_f16_f32 v45, v16, v17
	v_lshl_add_u64 v[16:17], v[38:39], 0, v[158:159]
	v_pk_mul_f32 v[20:21], v[20:21], v[24:25]
	v_pk_mul_f32 v[24:25], v[36:37], v[32:33] op_sel_hi:[1,0]
	v_cvt_pk_f16_f32 v20, v20, v21
	v_pk_mul_f32 v[22:23], v[24:25], v[22:23]
	v_cvt_f32_f16_e32 v24, v53
	v_cvt_f32_f16_sdwa v25, v53 dst_sel:DWORD dst_unused:UNUSED_PAD src0_sel:WORD_1
	v_permlane32_swap_b32_e32 v18, v20
	v_mov_b32_e32 v41, v74
	v_pk_mul_f32 v[22:23], v[22:23], v[24:25]
	s_nop 0
	v_permlane32_swap_b32_e32 v72, v41
	v_cvt_pk_f16_f32 v21, v22, v23
	s_nop 1
	v_permlane32_swap_b32_e32 v19, v21
	global_store_dwordx4 v[16:17], v[18:21], off offset:1024 sc1
	ds_read_b128 v[18:21], v201 offset:128
	v_pk_mul_f32 v[6:7], v[6:7], v[32:33] op_sel_hi:[1,0]
	v_mov_b32_e32 v40, v75
	s_nop 1
	v_permlane32_swap_b32_e32 v73, v40
	s_waitcnt lgkmcnt(0)
	v_pk_mul_f32 v[6:7], v[6:7], v[18:19]
	v_cvt_f32_f16_e32 v18, v72
	v_cvt_f32_f16_sdwa v19, v72 dst_sel:DWORD dst_unused:UNUSED_PAD src0_sel:WORD_1
	v_pk_mul_f32 v[4:5], v[4:5], v[32:33] op_sel_hi:[1,0]
	v_mov_b32_e32 v2, v71
	v_pk_mul_f32 v[4:5], v[4:5], v[20:21]
	v_pk_mul_f32 v[6:7], v[6:7], v[18:19]
	v_cvt_f32_f16_e32 v18, v73
	v_cvt_f32_f16_sdwa v19, v73 dst_sel:DWORD dst_unused:UNUSED_PAD src0_sel:WORD_1
	v_cvt_pk_f16_f32 v6, v6, v7
	v_permlane32_swap_b32_e32 v69, v2
	v_pk_mul_f32 v[4:5], v[4:5], v[18:19]
	ds_read_b128 v[18:21], v201 offset:160
	v_cvt_pk_f16_f32 v7, v4, v5
	v_pk_mul_f32 v[4:5], v[8:9], v[32:33] op_sel_hi:[1,0]
	v_cvt_f32_f16_e32 v8, v41
	v_cvt_f32_f16_sdwa v9, v41 dst_sel:DWORD dst_unused:UNUSED_PAD src0_sel:WORD_1
	s_waitcnt lgkmcnt(0)
	v_pk_mul_f32 v[4:5], v[4:5], v[18:19]
	v_permlane32_swap_b32_e32 v42, v44
	v_pk_mul_f32 v[4:5], v[4:5], v[8:9]
	v_permlane32_swap_b32_e32 v43, v45
	v_cvt_pk_f16_f32 v8, v4, v5
	v_pk_mul_f32 v[4:5], v[10:11], v[32:33] op_sel_hi:[1,0]
	v_cvt_f32_f16_e32 v10, v40
	v_cvt_f32_f16_sdwa v11, v40 dst_sel:DWORD dst_unused:UNUSED_PAD src0_sel:WORD_1
	v_pk_mul_f32 v[4:5], v[4:5], v[20:21]
	v_permlane32_swap_b32_e32 v6, v8
	v_pk_mul_f32 v[4:5], v[4:5], v[10:11]
	v_pk_mul_f32 v[10:11], v[26:27], v[32:33] op_sel_hi:[1,0]
	v_cvt_pk_f16_f32 v9, v4, v5
	s_nop 1
	v_permlane32_swap_b32_e32 v7, v9
	global_store_dwordx4 v[16:17], v[6:9], off offset:2048 sc1
	ds_read_b128 v[4:7], v201 offset:192
	s_andn2_b64 vcc, exec, s[50:51]
	v_pk_mul_f32 v[8:9], v[14:15], v[32:33] op_sel_hi:[1,0]
	s_mov_b32 s6, s52
	s_mov_b32 s0, s54
	s_waitcnt lgkmcnt(0)
	v_pk_mul_f32 v[4:5], v[8:9], v[4:5]
	v_cvt_f32_f16_e32 v8, v68
	v_cvt_f32_f16_sdwa v9, v68 dst_sel:DWORD dst_unused:UNUSED_PAD src0_sel:WORD_1
	s_mov_b32 s10, s28
	s_mov_b32 s20, s29
	v_mov_b64_e32 v[166:167], v[162:163]
	v_pk_mul_f32 v[4:5], v[4:5], v[8:9]
	v_pk_mul_f32 v[8:9], v[12:13], v[32:33] op_sel_hi:[1,0]
	v_cvt_pk_f16_f32 v4, v4, v5
	v_pk_mul_f32 v[6:7], v[8:9], v[6:7]
	v_cvt_f32_f16_e32 v8, v69
	v_cvt_f32_f16_sdwa v9, v69 dst_sel:DWORD dst_unused:UNUSED_PAD src0_sel:WORD_1
	v_mov_b64_e32 v[164:165], v[160:161]
	global_store_dwordx4 v[16:17], v[42:45], off sc1
	v_pk_mul_f32 v[6:7], v[6:7], v[8:9]
	s_nop 0
	v_cvt_pk_f16_f32 v5, v6, v7
	ds_read_b128 v[6:9], v201 offset:224
	s_waitcnt lgkmcnt(0)
	v_pk_mul_f32 v[6:7], v[10:11], v[6:7]
	v_cvt_f32_f16_e32 v10, v33
	v_cvt_f32_f16_sdwa v11, v33 dst_sel:DWORD dst_unused:UNUSED_PAD src0_sel:WORD_1
	v_pk_mul_f32 v[6:7], v[6:7], v[10:11]
	v_pk_mul_f32 v[10:11], v[28:29], v[32:33] op_sel_hi:[1,0]
	v_cvt_pk_f16_f32 v6, v6, v7
	v_pk_mul_f32 v[8:9], v[10:11], v[8:9]
	v_cvt_f32_f16_e32 v10, v2
	v_cvt_f32_f16_sdwa v11, v2 dst_sel:DWORD dst_unused:UNUSED_PAD src0_sel:WORD_1
	v_permlane32_swap_b32_e32 v4, v6
	v_pk_mul_f32 v[8:9], v[8:9], v[10:11]
	s_nop 0
	v_cvt_pk_f16_f32 v7, v8, v9
	s_nop 1
	v_permlane32_swap_b32_e32 v5, v7
	global_store_dwordx4 v[16:17], v[4:7], off offset:3072 sc1
	s_cbranch_vccz .LBB0_530

; #define GAS __attribute__((address_space(1)))
; __host__ __device__ __forceinline__ size_t bl1024(size_t row, int col) { return ((row >> 5) * 128 + (size_t)(col >> 3)) * 256 + (row & 31) * 8 + (col & 7); }
; __device__ __forceinline__ void sb_phase(LAS unsigned char* lds, const GAS f16* __restrict__ kv, const GAS f16* __restrict__ qg, GAS f16* __restrict__ mixed, int vcu, int G, unsigned long long& sw_acc) {
;     ...
;         {
;             GAS f16* Op = mixed + bl1024(grow, h * 64);
;             u32x2 gv[8]; unpack_groups(gr, gv);
; #pragma unroll
;             for (int d0 = 0; d0 < 2; ++d0)
; #pragma unroll
;                 for (int pr = 0; pr < 2; ++pr) {
;                     u32x2 wv[2];
; #pragma unroll
;                     for (int e = 0; e < 2; ++e) { const int rg4 = 2 * pr + e; const h4 g = __builtin_bit_cast(h4, gv[d0 * 4 + rg4]);
;                         wv[e].x = pkh(o[d0][4 * rg4] * (float)g[0], o[d0][4 * rg4 + 1] * (float)g[1]); wv[e].y = pkh(o[d0][4 * rg4 + 2] * (float)g[2], o[d0][4 * rg4 + 3] * (float)g[3]); }
;                     st_groups2_bl(Op, hi, 2 * d0 + pr, wv[0], wv[1]);
;                 }
;         }
;         if (!has_next) break;
.LBB0_536:
	s_and_b64 s[34:35], s[42:43], exec
	s_cselect_b32 s76, s53, s50
	s_ashr_i32 s29, s28, 31
	s_lshl_b64 s[28:29], s[28:29], 11
	s_ashr_i32 s31, s85, 31
	s_add_u32 s28, s28, s85
	s_addc_u32 s29, s29, s31
	s_lshl_b32 s1, s1, 8
	s_or_b32 s1, s1, s15
	v_or_b32_e32 v2, s28, v116
	s_lshl_b64 s[28:29], s[28:29], 2
	s_ashr_i32 s1, s1, 3
	s_and_b32 s29, s29, 0x7fffff
	s_and_b32 s28, s28, 0xffffff80
	s_ashr_i32 s31, s1, 31
	s_add_u32 s28, s28, s1
	s_addc_u32 s29, s29, s31
	s_lshl_b64 s[28:29], s[28:29], 9
	s_add_u32 s28, s33, s28
	v_lshlrev_b32_e32 v2, 4, v2
	s_addc_u32 s29, s26, s29
	v_and_b32_e32 v2, 0x1f0, v2
	v_lshl_add_u64 v[42:43], s[28:29], 0, v[2:3]
	v_mov_b32_e32 v2, v98
	s_nop 1
	v_permlane32_swap_b32_e32 v96, v2
	v_cvt_f32_f16_e32 v38, v96
	v_cvt_f32_f16_sdwa v39, v96 dst_sel:DWORD dst_unused:UNUSED_PAD src0_sel:WORD_1
	v_mov_b32_e32 v37, v99
	s_nop 1
	v_permlane32_swap_b32_e32 v97, v37
	v_pk_mul_f32 v[20:21], v[20:21], v[38:39]
	v_mov_b32_e32 v44, v94
	v_cvt_pk_f16_f32 v38, v20, v21
	v_cvt_f32_f16_e32 v20, v97
	v_cvt_f32_f16_sdwa v21, v97 dst_sel:DWORD dst_unused:UNUSED_PAD src0_sel:WORD_1
	v_mov_b32_e32 v45, v95
	v_permlane32_swap_b32_e32 v92, v44
	v_pk_mul_f32 v[20:21], v[22:23], v[20:21]
	v_permlane32_swap_b32_e32 v93, v45
	v_cvt_pk_f16_f32 v39, v20, v21
	v_cvt_f32_f16_e32 v20, v2
	v_cvt_f32_f16_sdwa v21, v2 dst_sel:DWORD dst_unused:UNUSED_PAD src0_sel:WORD_1
	v_cvt_f32_f16_e32 v22, v92
	v_cvt_f32_f16_sdwa v23, v92 dst_sel:DWORD dst_unused:UNUSED_PAD src0_sel:WORD_1
	v_mov_b32_e32 v46, v90
	v_pk_mul_f32 v[20:21], v[24:25], v[20:21]
	v_cvt_f32_f16_e32 v24, v93
	v_cvt_f32_f16_sdwa v25, v93 dst_sel:DWORD dst_unused:UNUSED_PAD src0_sel:WORD_1
	v_cvt_pk_f16_f32 v40, v20, v21
	v_cvt_f32_f16_e32 v20, v37
	v_cvt_f32_f16_sdwa v21, v37 dst_sel:DWORD dst_unused:UNUSED_PAD src0_sel:WORD_1
	v_pk_mul_f32 v[22:23], v[28:29], v[22:23]
	v_pk_mul_f32 v[24:25], v[30:31], v[24:25]
	v_cvt_pk_f16_f32 v22, v22, v23
	v_pk_mul_f32 v[20:21], v[26:27], v[20:21]
	v_cvt_pk_f16_f32 v23, v24, v25
	v_cvt_f32_f16_e32 v24, v44
	v_cvt_f32_f16_sdwa v25, v44 dst_sel:DWORD dst_unused:UNUSED_PAD src0_sel:WORD_1
	v_cvt_f32_f16_e32 v26, v45
	v_cvt_f32_f16_sdwa v27, v45 dst_sel:DWORD dst_unused:UNUSED_PAD src0_sel:WORD_1
	v_mov_b32_e32 v37, v3
	v_pk_mul_f32 v[24:25], v[32:33], v[24:25]
	v_permlane32_swap_b32_e32 v88, v46
	v_pk_mul_f32 v[26:27], v[34:35], v[26:27]
	v_cvt_pk_f16_f32 v24, v24, v25
	v_cvt_pk_f16_f32 v25, v26, v27
	v_cvt_pk_f16_f32 v41, v20, v21
	v_lshl_add_u64 v[20:21], v[42:43], 0, v[36:37]
	v_permlane32_swap_b32_e32 v22, v24
	v_permlane32_swap_b32_e32 v23, v25
	global_store_dwordx4 v[20:21], v[22:25], off offset:1024 sc1
	v_mov_b32_e32 v47, v91
	s_nop 1
	v_permlane32_swap_b32_e32 v89, v47
	v_cvt_f32_f16_e32 v22, v88
	v_cvt_f32_f16_sdwa v23, v88 dst_sel:DWORD dst_unused:UNUSED_PAD src0_sel:WORD_1
	v_mov_b32_e32 v48, v86
	v_mov_b32_e32 v49, v87
	s_nop 0
	v_permlane32_swap_b32_e32 v84, v48
	v_pk_mul_f32 v[4:5], v[4:5], v[22:23]
	v_cvt_f32_f16_e32 v22, v89
	v_cvt_f32_f16_sdwa v23, v89 dst_sel:DWORD dst_unused:UNUSED_PAD src0_sel:WORD_1
	v_cvt_pk_f16_f32 v4, v4, v5
	v_permlane32_swap_b32_e32 v85, v49
	v_pk_mul_f32 v[6:7], v[6:7], v[22:23]
	s_mov_b32 s77, 0x2081cea
	v_cvt_pk_f16_f32 v5, v6, v7
	v_cvt_f32_f16_e32 v6, v46
	v_cvt_f32_f16_sdwa v7, v46 dst_sel:DWORD dst_unused:UNUSED_PAD src0_sel:WORD_1
	v_permlane32_swap_b32_e32 v38, v40
	v_permlane32_swap_b32_e32 v39, v41
	v_pk_mul_f32 v[6:7], v[8:9], v[6:7]
	v_cvt_f32_f16_e32 v8, v47
	v_cvt_f32_f16_sdwa v9, v47 dst_sel:DWORD dst_unused:UNUSED_PAD src0_sel:WORD_1
	v_cvt_pk_f16_f32 v6, v6, v7
	s_nop 1
	v_permlane32_swap_b32_e32 v4, v6
	v_pk_mul_f32 v[8:9], v[10:11], v[8:9]
	s_andn2_b64 vcc, exec, s[24:25]
	v_cvt_pk_f16_f32 v7, v8, v9
	s_nop 1
	v_permlane32_swap_b32_e32 v5, v7
	global_store_dwordx4 v[20:21], v[4:7], off offset:2048 sc1
	v_cvt_f32_f16_e32 v8, v49
	v_cvt_f32_f16_sdwa v9, v49 dst_sel:DWORD dst_unused:UNUSED_PAD src0_sel:WORD_1
	v_cvt_f32_f16_e32 v4, v84
	v_cvt_f32_f16_sdwa v5, v84 dst_sel:DWORD dst_unused:UNUSED_PAD src0_sel:WORD_1
	v_cvt_f32_f16_e32 v6, v85
	v_cvt_f32_f16_sdwa v7, v85 dst_sel:DWORD dst_unused:UNUSED_PAD src0_sel:WORD_1
	v_pk_mul_f32 v[8:9], v[18:19], v[8:9]
	v_pk_mul_f32 v[4:5], v[12:13], v[4:5]
	s_mov_b32 s29, s18
	v_pk_mul_f32 v[6:7], v[14:15], v[6:7]
	v_cvt_pk_f16_f32 v4, v4, v5
	v_cvt_pk_f16_f32 v5, v6, v7
	v_cvt_f32_f16_e32 v6, v48
	v_cvt_f32_f16_sdwa v7, v48 dst_sel:DWORD dst_unused:UNUSED_PAD src0_sel:WORD_1
	s_mov_b32 s1, s84
	s_mov_b32 s28, s30
	s_mov_b32 s50, s19
	v_pk_mul_f32 v[6:7], v[16:17], v[6:7]
	global_store_dwordx4 v[20:21], v[38:41], off sc1
	v_cvt_pk_f16_f32 v6, v6, v7
	v_cvt_pk_f16_f32 v7, v8, v9
	s_nop 0
	v_permlane32_swap_b32_e32 v4, v6
	v_permlane32_swap_b32_e32 v5, v7
	global_store_dwordx4 v[20:21], v[4:7], off offset:3072 sc1
	s_cbranch_vccz .LBB0_584
